# v011 + nt on GEMM2 GA/GB loads (hook and epilogue)
# speedup vs baseline: 1.0051x; 1.0005x over previous
;     __device__ __forceinline__ void mid(f32x4 (&acc)[2][2][4][2], const pg8::Unit& u, int wr, int wc, int fr, int fq) const {
;         int row0 = u.pm * 256 + wr * 64 + fr, col0 = u.pn * 256 + wc * 32 + 8 * fq;
;         asm volatile("" : "+v"(row0), "+v"(col0));
; #pragma unroll
;         for (int ai = 0; ai < 2; ++ai)
; #pragma unroll
;             for (int m = 0; m < 4; ++m) {
;                 const size_t off = (size_t)(row0 + ai * 128 + m * 16) * DM + col0;
; #pragma unroll
;                 for (int bj = 0; bj < 2; ++bj) {
;                     const u32x4 ga = *(const u32x4*)(GA + off + bj * 128), gb = *(const u32x4*)(GB + off + bj * 128);
;                     acc[ai][bj][m][0][0] *= bflo(ga.x) * __builtin_amdgcn_rcpf(bflo(gb.x)); acc[ai][bj][m][0][1] *= bfhi(ga.x) * __builtin_amdgcn_rcpf(bfhi(gb.x));
;                     acc[ai][bj][m][0][2] *= bflo(ga.y) * __builtin_amdgcn_rcpf(bflo(gb.y)); acc[ai][bj][m][0][3] *= bfhi(ga.y) * __builtin_amdgcn_rcpf(bfhi(gb.y));
;                     acc[ai][bj][m][1][0] *= bflo(ga.z) * __builtin_amdgcn_rcpf(bflo(gb.z)); acc[ai][bj][m][1][1] *= bfhi(ga.z) * __builtin_amdgcn_rcpf(bfhi(gb.z));
;                     acc[ai][bj][m][1][2] *= bflo(ga.w) * __builtin_amdgcn_rcpf(bflo(gb.w)); acc[ai][bj][m][1][3] *= bfhi(ga.w) * __builtin_amdgcn_rcpf(bfhi(gb.w));
;                     asm volatile("" : "+v"(acc[ai][bj][m][0]), "+v"(acc[ai][bj][m][1]));
;                     asm volatile("" ::: "memory");
;                 }
;             }
;     }
.LBB0_455:
	v_mov_b32_e32 v2, v146
	v_mov_b32_e32 v208, v147
	s_andn2_b64 vcc, exec, s[12:13]
	v_ashrrev_i32_e32 v3, 31, v2
	v_ashrrev_i32_e32 v209, 31, v208
	v_lshlrev_b64 v[2:3], 12, v[2:3]
	v_lshl_add_u64 v[2:3], v[2:3], 0, v[208:209]
	v_lshlrev_b64 v[2:3], 1, v[2:3]
	v_lshl_add_u64 v[204:205], s[16:17], 0, v[2:3]
	v_lshl_add_u64 v[206:207], s[14:15], 0, v[2:3]
	global_load_dwordx4 v[148:151], v[204:205], off nt
	global_load_dwordx4 v[152:155], v[206:207], off nt
	global_load_dwordx4 v[156:159], v[204:205], off offset:256 nt
	global_load_dwordx4 v[160:163], v[206:207], off offset:256 nt
	v_lshl_add_u64 v[208:209], v[2:3], 0, s[40:41]
	v_lshl_add_u64 v[204:205], s[16:17], 0, v[208:209]
	v_lshl_add_u64 v[206:207], s[14:15], 0, v[208:209]
	global_load_dwordx4 v[164:167], v[204:205], off nt
	global_load_dwordx4 v[168:171], v[206:207], off nt
	global_load_dwordx4 v[172:175], v[204:205], off offset:256 nt
	global_load_dwordx4 v[176:179], v[206:207], off offset:256 nt
	v_lshl_add_u64 v[208:209], v[2:3], 0, s[42:43]
	v_lshl_add_u64 v[204:205], s[16:17], 0, v[208:209]
	v_lshl_add_u64 v[206:207], s[14:15], 0, v[208:209]
	global_load_dwordx4 v[180:183], v[204:205], off nt
	global_load_dwordx4 v[184:187], v[206:207], off nt
	global_load_dwordx4 v[188:191], v[204:205], off offset:256 nt
	global_load_dwordx4 v[192:195], v[206:207], off offset:256 nt
	v_lshl_add_u64 v[208:209], v[2:3], 0, s[44:45]
	v_lshl_add_u64 v[204:205], s[16:17], 0, v[208:209]
	v_lshl_add_u64 v[206:207], s[14:15], 0, v[208:209]
	global_load_dwordx4 v[196:199], v[204:205], off nt
	global_load_dwordx4 v[200:203], v[206:207], off nt
	global_load_dwordx4 v[212:215], v[204:205], off offset:256 nt
	global_load_dwordx4 v[216:219], v[206:207], off offset:256 nt
	v_lshl_add_u64 v[208:209], v[2:3], 0, s[8:9]
	v_lshl_add_u64 v[204:205], s[16:17], 0, v[208:209]
	v_lshl_add_u64 v[206:207], s[14:15], 0, v[208:209]
	global_load_dwordx4 v[220:223], v[204:205], off nt
	global_load_dwordx4 v[224:227], v[206:207], off nt
	global_load_dwordx4 v[228:231], v[204:205], off offset:256 nt
	global_load_dwordx4 v[232:235], v[206:207], off offset:256 nt
	s_waitcnt vmcnt(18)
	v_lshlrev_b32_e32 v236, 16, v148
	v_and_b32_e32 v237, 0xffff0000, v148
	v_lshlrev_b32_e32 v238, 16, v149
	v_and_b32_e32 v239, 0xffff0000, v149
	v_lshlrev_b32_e32 v240, 16, v150
	v_and_b32_e32 v241, 0xffff0000, v150
	v_lshlrev_b32_e32 v242, 16, v151
	v_and_b32_e32 v243, 0xffff0000, v151
	v_lshlrev_b32_e32 v244, 16, v152
	v_and_b32_e32 v245, 0xffff0000, v152
	v_lshlrev_b32_e32 v246, 16, v153
	v_and_b32_e32 v247, 0xffff0000, v153
	v_lshlrev_b32_e32 v248, 16, v154
	v_and_b32_e32 v249, 0xffff0000, v154
	v_lshlrev_b32_e32 v250, 16, v155
	v_and_b32_e32 v251, 0xffff0000, v155
	v_lshl_add_u64 v[208:209], v[2:3], 0, s[46:47]
	v_lshl_add_u64 v[204:205], s[16:17], 0, v[208:209]
	v_lshl_add_u64 v[206:207], s[14:15], 0, v[208:209]
	global_load_dwordx4 v[148:151], v[204:205], off nt
	global_load_dwordx4 v[152:155], v[206:207], off nt
	v_rcp_f32_e32 v236, v236
	v_rcp_f32_e32 v237, v237
	v_rcp_f32_e32 v238, v238
	v_rcp_f32_e32 v239, v239
	v_rcp_f32_e32 v240, v240
	v_rcp_f32_e32 v241, v241
	v_rcp_f32_e32 v242, v242
	v_rcp_f32_e32 v243, v243
	v_pk_mul_f32 v[244:245], v[236:237], v[244:245]
	v_pk_mul_f32 v[246:247], v[238:239], v[246:247]
	v_pk_mul_f32 v[248:249], v[240:241], v[248:249]
	v_pk_mul_f32 v[250:251], v[242:243], v[250:251]
	v_pk_mul_f32 v[128:129], v[128:129], v[244:245]
	v_pk_mul_f32 v[130:131], v[130:131], v[246:247]
	v_pk_mul_f32 v[124:125], v[124:125], v[248:249]
	v_pk_mul_f32 v[126:127], v[126:127], v[250:251]
	s_nop 0
	s_waitcnt vmcnt(18)
	v_lshlrev_b32_e32 v236, 16, v156
	v_and_b32_e32 v237, 0xffff0000, v156
	v_lshlrev_b32_e32 v238, 16, v157
	v_and_b32_e32 v239, 0xffff0000, v157
	v_lshlrev_b32_e32 v240, 16, v158
	v_and_b32_e32 v241, 0xffff0000, v158
	v_lshlrev_b32_e32 v242, 16, v159
	v_and_b32_e32 v243, 0xffff0000, v159
	v_lshlrev_b32_e32 v244, 16, v160
	v_and_b32_e32 v245, 0xffff0000, v160
	v_lshlrev_b32_e32 v246, 16, v161
	v_and_b32_e32 v247, 0xffff0000, v161
	v_lshlrev_b32_e32 v248, 16, v162
	v_and_b32_e32 v249, 0xffff0000, v162
	v_lshlrev_b32_e32 v250, 16, v163
	v_and_b32_e32 v251, 0xffff0000, v163
	global_load_dwordx4 v[156:159], v[204:205], off offset:256 nt
	global_load_dwordx4 v[160:163], v[206:207], off offset:256 nt
	v_rcp_f32_e32 v236, v236
	v_rcp_f32_e32 v237, v237
	v_rcp_f32_e32 v238, v238
	v_rcp_f32_e32 v239, v239
	v_rcp_f32_e32 v240, v240
	v_rcp_f32_e32 v241, v241
	v_rcp_f32_e32 v242, v242
	v_rcp_f32_e32 v243, v243
	v_pk_mul_f32 v[244:245], v[236:237], v[244:245]
	v_pk_mul_f32 v[246:247], v[238:239], v[246:247]
	v_pk_mul_f32 v[248:249], v[240:241], v[248:249]
	v_pk_mul_f32 v[250:251], v[242:243], v[250:251]
	v_pk_mul_f32 v[120:121], v[120:121], v[244:245]
	v_pk_mul_f32 v[122:123], v[122:123], v[246:247]
	v_pk_mul_f32 v[116:117], v[116:117], v[248:249]
	v_pk_mul_f32 v[118:119], v[118:119], v[250:251]
	s_nop 0
	s_waitcnt vmcnt(18)
;     __device__ __forceinline__ void mid(f32x4 (&acc)[2][2][4][2], const pg8::Unit& u, int wr, int wc, int fr, int fq) const {
;     ...
;                     const u32x4 ga = *(const u32x4*)(GA + off + bj * 128), gb = *(const u32x4*)(GB + off + bj * 128);
;                     acc[ai][bj][m][0][0] *= bflo(ga.x) * __builtin_amdgcn_rcpf(bflo(gb.x)); acc[ai][bj][m][0][1] *= bfhi(ga.x) * __builtin_amdgcn_rcpf(bfhi(gb.x));
;                     acc[ai][bj][m][0][2] *= bflo(ga.y) * __builtin_amdgcn_rcpf(bflo(gb.y)); acc[ai][bj][m][0][3] *= bfhi(ga.y) * __builtin_amdgcn_rcpf(bfhi(gb.y));
;                     acc[ai][bj][m][1][0] *= bflo(ga.z) * __builtin_amdgcn_rcpf(bflo(gb.z)); acc[ai][bj][m][1][1] *= bfhi(ga.z) * __builtin_amdgcn_rcpf(bfhi(gb.z));
;                     acc[ai][bj][m][1][2] *= bflo(ga.w) * __builtin_amdgcn_rcpf(bflo(gb.w)); acc[ai][bj][m][1][3] *= bfhi(ga.w) * __builtin_amdgcn_rcpf(bfhi(gb.w));
;                     asm volatile("" : "+v"(acc[ai][bj][m][0]), "+v"(acc[ai][bj][m][1]));
	v_lshlrev_b32_e32 v236, 16, v164
	v_and_b32_e32 v237, 0xffff0000, v164
	v_lshlrev_b32_e32 v238, 16, v165
	v_and_b32_e32 v239, 0xffff0000, v165
	v_lshlrev_b32_e32 v240, 16, v166
	v_and_b32_e32 v241, 0xffff0000, v166
	v_lshlrev_b32_e32 v242, 16, v167
	v_and_b32_e32 v243, 0xffff0000, v167
	v_lshlrev_b32_e32 v244, 16, v168
	v_and_b32_e32 v245, 0xffff0000, v168
	v_lshlrev_b32_e32 v246, 16, v169
	v_and_b32_e32 v247, 0xffff0000, v169
	v_lshlrev_b32_e32 v248, 16, v170
	v_and_b32_e32 v249, 0xffff0000, v170
	v_lshlrev_b32_e32 v250, 16, v171
	v_and_b32_e32 v251, 0xffff0000, v171
	v_lshl_add_u64 v[208:209], v[2:3], 0, s[48:49]
	v_lshl_add_u64 v[204:205], s[16:17], 0, v[208:209]
	v_lshl_add_u64 v[206:207], s[14:15], 0, v[208:209]
	global_load_dwordx4 v[164:167], v[204:205], off nt
	global_load_dwordx4 v[168:171], v[206:207], off nt
	v_rcp_f32_e32 v236, v236
	v_rcp_f32_e32 v237, v237
	v_rcp_f32_e32 v238, v238
	v_rcp_f32_e32 v239, v239
	v_rcp_f32_e32 v240, v240
	v_rcp_f32_e32 v241, v241
	v_rcp_f32_e32 v242, v242
	v_rcp_f32_e32 v243, v243
	v_pk_mul_f32 v[244:245], v[236:237], v[244:245]
	v_pk_mul_f32 v[246:247], v[238:239], v[246:247]
	v_pk_mul_f32 v[248:249], v[240:241], v[248:249]
	v_pk_mul_f32 v[250:251], v[242:243], v[250:251]
	v_pk_mul_f32 v[112:113], v[112:113], v[244:245]
	v_pk_mul_f32 v[114:115], v[114:115], v[246:247]
	v_pk_mul_f32 v[108:109], v[108:109], v[248:249]
	v_pk_mul_f32 v[110:111], v[110:111], v[250:251]
	s_nop 0
	s_waitcnt vmcnt(18)
	v_lshlrev_b32_e32 v236, 16, v172
	v_and_b32_e32 v237, 0xffff0000, v172
	v_lshlrev_b32_e32 v238, 16, v173
	v_and_b32_e32 v239, 0xffff0000, v173
	v_lshlrev_b32_e32 v240, 16, v174
	v_and_b32_e32 v241, 0xffff0000, v174
	v_lshlrev_b32_e32 v242, 16, v175
	v_and_b32_e32 v243, 0xffff0000, v175
	v_lshlrev_b32_e32 v244, 16, v176
	v_and_b32_e32 v245, 0xffff0000, v176
	v_lshlrev_b32_e32 v246, 16, v177
	v_and_b32_e32 v247, 0xffff0000, v177
	v_lshlrev_b32_e32 v248, 16, v178
	v_and_b32_e32 v249, 0xffff0000, v178
	v_lshlrev_b32_e32 v250, 16, v179
	v_and_b32_e32 v251, 0xffff0000, v179
	global_load_dwordx4 v[172:175], v[204:205], off offset:256 nt
	global_load_dwordx4 v[176:179], v[206:207], off offset:256 nt
	v_rcp_f32_e32 v236, v236
	v_rcp_f32_e32 v237, v237
	v_rcp_f32_e32 v238, v238
	v_rcp_f32_e32 v239, v239
	v_rcp_f32_e32 v240, v240
	v_rcp_f32_e32 v241, v241
	v_rcp_f32_e32 v242, v242
	v_rcp_f32_e32 v243, v243
	v_pk_mul_f32 v[244:245], v[236:237], v[244:245]
	v_pk_mul_f32 v[246:247], v[238:239], v[246:247]
	v_pk_mul_f32 v[248:249], v[240:241], v[248:249]
	v_pk_mul_f32 v[250:251], v[242:243], v[250:251]
	v_pk_mul_f32 v[104:105], v[104:105], v[244:245]
	v_pk_mul_f32 v[106:107], v[106:107], v[246:247]
	v_pk_mul_f32 v[100:101], v[100:101], v[248:249]
	v_pk_mul_f32 v[102:103], v[102:103], v[250:251]
	s_nop 0
	s_waitcnt vmcnt(18)
	v_lshlrev_b32_e32 v236, 16, v180
	v_and_b32_e32 v237, 0xffff0000, v180
	v_lshlrev_b32_e32 v238, 16, v181
	v_and_b32_e32 v239, 0xffff0000, v181
	v_lshlrev_b32_e32 v240, 16, v182
	v_and_b32_e32 v241, 0xffff0000, v182
	v_lshlrev_b32_e32 v242, 16, v183
	v_and_b32_e32 v243, 0xffff0000, v183
	v_lshlrev_b32_e32 v244, 16, v184
	v_and_b32_e32 v245, 0xffff0000, v184
	v_lshlrev_b32_e32 v246, 16, v185
	v_and_b32_e32 v247, 0xffff0000, v185
	v_lshlrev_b32_e32 v248, 16, v186
	v_and_b32_e32 v249, 0xffff0000, v186
	v_lshlrev_b32_e32 v250, 16, v187
	v_and_b32_e32 v251, 0xffff0000, v187
	v_lshl_add_u64 v[208:209], v[2:3], 0, s[50:51]
	v_lshl_add_u64 v[204:205], s[16:17], 0, v[208:209]
	v_lshl_add_u64 v[206:207], s[14:15], 0, v[208:209]
	global_load_dwordx4 v[180:183], v[204:205], off nt
	global_load_dwordx4 v[184:187], v[206:207], off nt
	v_rcp_f32_e32 v236, v236
	v_rcp_f32_e32 v237, v237
	v_rcp_f32_e32 v238, v238
	v_rcp_f32_e32 v239, v239
	v_rcp_f32_e32 v240, v240
	v_rcp_f32_e32 v241, v241
	v_rcp_f32_e32 v242, v242
	v_rcp_f32_e32 v243, v243
	v_pk_mul_f32 v[244:245], v[236:237], v[244:245]
	v_pk_mul_f32 v[246:247], v[238:239], v[246:247]
	v_pk_mul_f32 v[248:249], v[240:241], v[248:249]
	v_pk_mul_f32 v[250:251], v[242:243], v[250:251]
	v_pk_mul_f32 v[96:97], v[96:97], v[244:245]
	v_pk_mul_f32 v[98:99], v[98:99], v[246:247]
	v_pk_mul_f32 v[92:93], v[92:93], v[248:249]
	v_pk_mul_f32 v[94:95], v[94:95], v[250:251]
	s_nop 0
	s_waitcnt vmcnt(18)
	v_lshlrev_b32_e32 v236, 16, v188
	v_and_b32_e32 v237, 0xffff0000, v188
	v_lshlrev_b32_e32 v238, 16, v189
	v_and_b32_e32 v239, 0xffff0000, v189
	v_lshlrev_b32_e32 v240, 16, v190
	v_and_b32_e32 v241, 0xffff0000, v190
	v_lshlrev_b32_e32 v242, 16, v191
	v_and_b32_e32 v243, 0xffff0000, v191
	v_lshlrev_b32_e32 v244, 16, v192
	v_and_b32_e32 v245, 0xffff0000, v192
	v_lshlrev_b32_e32 v246, 16, v193
	v_and_b32_e32 v247, 0xffff0000, v193
	v_lshlrev_b32_e32 v248, 16, v194
	v_and_b32_e32 v249, 0xffff0000, v194
	v_lshlrev_b32_e32 v250, 16, v195
	v_and_b32_e32 v251, 0xffff0000, v195
	global_load_dwordx4 v[188:191], v[204:205], off offset:256 nt
	global_load_dwordx4 v[192:195], v[206:207], off offset:256 nt
	v_rcp_f32_e32 v236, v236
	v_rcp_f32_e32 v237, v237
	v_rcp_f32_e32 v238, v238
	v_rcp_f32_e32 v239, v239
	v_rcp_f32_e32 v240, v240
	v_rcp_f32_e32 v241, v241
	v_rcp_f32_e32 v242, v242
	v_rcp_f32_e32 v243, v243
	v_pk_mul_f32 v[244:245], v[236:237], v[244:245]
	v_pk_mul_f32 v[246:247], v[238:239], v[246:247]
	v_pk_mul_f32 v[248:249], v[240:241], v[248:249]
	v_pk_mul_f32 v[250:251], v[242:243], v[250:251]
	v_pk_mul_f32 v[88:89], v[88:89], v[244:245]
	v_pk_mul_f32 v[90:91], v[90:91], v[246:247]
	v_pk_mul_f32 v[84:85], v[84:85], v[248:249]
	v_pk_mul_f32 v[86:87], v[86:87], v[250:251]
	s_nop 0
	s_waitcnt vmcnt(18)
;     __device__ __forceinline__ void mid(f32x4 (&acc)[2][2][4][2], const pg8::Unit& u, int wr, int wc, int fr, int fq) const {
;     ...
;                     const u32x4 ga = *(const u32x4*)(GA + off + bj * 128), gb = *(const u32x4*)(GB + off + bj * 128);
;                     acc[ai][bj][m][0][0] *= bflo(ga.x) * __builtin_amdgcn_rcpf(bflo(gb.x)); acc[ai][bj][m][0][1] *= bfhi(ga.x) * __builtin_amdgcn_rcpf(bfhi(gb.x));
;                     acc[ai][bj][m][0][2] *= bflo(ga.y) * __builtin_amdgcn_rcpf(bflo(gb.y)); acc[ai][bj][m][0][3] *= bfhi(ga.y) * __builtin_amdgcn_rcpf(bfhi(gb.y));
;                     acc[ai][bj][m][1][0] *= bflo(ga.z) * __builtin_amdgcn_rcpf(bflo(gb.z)); acc[ai][bj][m][1][1] *= bfhi(ga.z) * __builtin_amdgcn_rcpf(bfhi(gb.z));
;                     acc[ai][bj][m][1][2] *= bflo(ga.w) * __builtin_amdgcn_rcpf(bflo(gb.w)); acc[ai][bj][m][1][3] *= bfhi(ga.w) * __builtin_amdgcn_rcpf(bfhi(gb.w));
;                     asm volatile("" : "+v"(acc[ai][bj][m][0]), "+v"(acc[ai][bj][m][1]));
	v_lshlrev_b32_e32 v236, 16, v196
	v_and_b32_e32 v237, 0xffff0000, v196
	v_lshlrev_b32_e32 v238, 16, v197
	v_and_b32_e32 v239, 0xffff0000, v197
	v_lshlrev_b32_e32 v240, 16, v198
	v_and_b32_e32 v241, 0xffff0000, v198
	v_lshlrev_b32_e32 v242, 16, v199
	v_and_b32_e32 v243, 0xffff0000, v199
	v_lshlrev_b32_e32 v244, 16, v200
	v_and_b32_e32 v245, 0xffff0000, v200
	v_lshlrev_b32_e32 v246, 16, v201
	v_and_b32_e32 v247, 0xffff0000, v201
	v_lshlrev_b32_e32 v248, 16, v202
	v_and_b32_e32 v249, 0xffff0000, v202
	v_lshlrev_b32_e32 v250, 16, v203
	v_and_b32_e32 v251, 0xffff0000, v203
	v_rcp_f32_e32 v236, v236
	v_rcp_f32_e32 v237, v237
	v_rcp_f32_e32 v238, v238
	v_rcp_f32_e32 v239, v239
	v_rcp_f32_e32 v240, v240
	v_rcp_f32_e32 v241, v241
	v_rcp_f32_e32 v242, v242
	v_rcp_f32_e32 v243, v243
	v_pk_mul_f32 v[244:245], v[236:237], v[244:245]
	v_pk_mul_f32 v[246:247], v[238:239], v[246:247]
	v_pk_mul_f32 v[248:249], v[240:241], v[248:249]
	v_pk_mul_f32 v[250:251], v[242:243], v[250:251]
	v_pk_mul_f32 v[80:81], v[80:81], v[244:245]
	v_pk_mul_f32 v[82:83], v[82:83], v[246:247]
	v_pk_mul_f32 v[76:77], v[76:77], v[248:249]
	v_pk_mul_f32 v[78:79], v[78:79], v[250:251]
	s_nop 0
	s_waitcnt vmcnt(16)
	v_lshlrev_b32_e32 v236, 16, v212
	v_and_b32_e32 v237, 0xffff0000, v212
	v_lshlrev_b32_e32 v238, 16, v213
	v_and_b32_e32 v239, 0xffff0000, v213
	v_lshlrev_b32_e32 v240, 16, v214
	v_and_b32_e32 v241, 0xffff0000, v214
	v_lshlrev_b32_e32 v242, 16, v215
	v_and_b32_e32 v243, 0xffff0000, v215
	v_lshlrev_b32_e32 v244, 16, v216
	v_and_b32_e32 v245, 0xffff0000, v216
	v_lshlrev_b32_e32 v246, 16, v217
	v_and_b32_e32 v247, 0xffff0000, v217
	v_lshlrev_b32_e32 v248, 16, v218
	v_and_b32_e32 v249, 0xffff0000, v218
	v_lshlrev_b32_e32 v250, 16, v219
	v_and_b32_e32 v251, 0xffff0000, v219
	v_rcp_f32_e32 v236, v236
	v_rcp_f32_e32 v237, v237
	v_rcp_f32_e32 v238, v238
	v_rcp_f32_e32 v239, v239
	v_rcp_f32_e32 v240, v240
	v_rcp_f32_e32 v241, v241
	v_rcp_f32_e32 v242, v242
	v_rcp_f32_e32 v243, v243
	v_pk_mul_f32 v[244:245], v[236:237], v[244:245]
	v_pk_mul_f32 v[246:247], v[238:239], v[246:247]
	v_pk_mul_f32 v[248:249], v[240:241], v[248:249]
	v_pk_mul_f32 v[250:251], v[242:243], v[250:251]
	v_pk_mul_f32 v[72:73], v[72:73], v[244:245]
	v_pk_mul_f32 v[74:75], v[74:75], v[246:247]
	v_pk_mul_f32 v[68:69], v[68:69], v[248:249]
	v_pk_mul_f32 v[70:71], v[70:71], v[250:251]
	s_nop 0
	s_waitcnt vmcnt(14)
	v_lshlrev_b32_e32 v236, 16, v220
	v_and_b32_e32 v237, 0xffff0000, v220
	v_lshlrev_b32_e32 v238, 16, v221
	v_and_b32_e32 v239, 0xffff0000, v221
	v_lshlrev_b32_e32 v240, 16, v222
	v_and_b32_e32 v241, 0xffff0000, v222
	v_lshlrev_b32_e32 v242, 16, v223
	v_and_b32_e32 v243, 0xffff0000, v223
	v_lshlrev_b32_e32 v244, 16, v224
	v_and_b32_e32 v245, 0xffff0000, v224
	v_lshlrev_b32_e32 v246, 16, v225
	v_and_b32_e32 v247, 0xffff0000, v225
	v_lshlrev_b32_e32 v248, 16, v226
	v_and_b32_e32 v249, 0xffff0000, v226
	v_lshlrev_b32_e32 v250, 16, v227
	v_and_b32_e32 v251, 0xffff0000, v227
	v_rcp_f32_e32 v236, v236
	v_rcp_f32_e32 v237, v237
	v_rcp_f32_e32 v238, v238
	v_rcp_f32_e32 v239, v239
	v_rcp_f32_e32 v240, v240
	v_rcp_f32_e32 v241, v241
	v_rcp_f32_e32 v242, v242
	v_rcp_f32_e32 v243, v243
	v_pk_mul_f32 v[244:245], v[236:237], v[244:245]
	v_pk_mul_f32 v[246:247], v[238:239], v[246:247]
	v_pk_mul_f32 v[248:249], v[240:241], v[248:249]
	v_pk_mul_f32 v[250:251], v[242:243], v[250:251]
	v_pk_mul_f32 v[64:65], v[64:65], v[244:245]
	v_pk_mul_f32 v[66:67], v[66:67], v[246:247]
	v_pk_mul_f32 v[60:61], v[60:61], v[248:249]
	v_pk_mul_f32 v[62:63], v[62:63], v[250:251]
	s_nop 0
	s_waitcnt vmcnt(12)
	v_lshlrev_b32_e32 v236, 16, v228
	v_and_b32_e32 v237, 0xffff0000, v228
	v_lshlrev_b32_e32 v238, 16, v229
	v_and_b32_e32 v239, 0xffff0000, v229
	v_lshlrev_b32_e32 v240, 16, v230
	v_and_b32_e32 v241, 0xffff0000, v230
	v_lshlrev_b32_e32 v242, 16, v231
	v_and_b32_e32 v243, 0xffff0000, v231
	v_lshlrev_b32_e32 v244, 16, v232
	v_and_b32_e32 v245, 0xffff0000, v232
	v_lshlrev_b32_e32 v246, 16, v233
	v_and_b32_e32 v247, 0xffff0000, v233
	v_lshlrev_b32_e32 v248, 16, v234
	v_and_b32_e32 v249, 0xffff0000, v234
	v_lshlrev_b32_e32 v250, 16, v235
	v_and_b32_e32 v251, 0xffff0000, v235
	v_rcp_f32_e32 v236, v236
	v_rcp_f32_e32 v237, v237
	v_rcp_f32_e32 v238, v238
	v_rcp_f32_e32 v239, v239
	v_rcp_f32_e32 v240, v240
	v_rcp_f32_e32 v241, v241
	v_rcp_f32_e32 v242, v242
	v_rcp_f32_e32 v243, v243
	v_pk_mul_f32 v[244:245], v[236:237], v[244:245]
	v_pk_mul_f32 v[246:247], v[238:239], v[246:247]
	v_pk_mul_f32 v[248:249], v[240:241], v[248:249]
	v_pk_mul_f32 v[250:251], v[242:243], v[250:251]
	v_pk_mul_f32 v[56:57], v[56:57], v[244:245]
	v_pk_mul_f32 v[58:59], v[58:59], v[246:247]
	v_pk_mul_f32 v[52:53], v[52:53], v[248:249]
	v_pk_mul_f32 v[54:55], v[54:55], v[250:251]
	s_nop 0
	s_waitcnt vmcnt(10)
	v_lshlrev_b32_e32 v236, 16, v148
	v_and_b32_e32 v237, 0xffff0000, v148
	v_lshlrev_b32_e32 v238, 16, v149
	v_and_b32_e32 v239, 0xffff0000, v149
	v_lshlrev_b32_e32 v240, 16, v150
	v_and_b32_e32 v241, 0xffff0000, v150
	v_lshlrev_b32_e32 v242, 16, v151
	v_and_b32_e32 v243, 0xffff0000, v151
	v_lshlrev_b32_e32 v244, 16, v152
	v_and_b32_e32 v245, 0xffff0000, v152
	v_lshlrev_b32_e32 v246, 16, v153
	v_and_b32_e32 v247, 0xffff0000, v153
	v_lshlrev_b32_e32 v248, 16, v154
	v_and_b32_e32 v249, 0xffff0000, v154
	v_lshlrev_b32_e32 v250, 16, v155
	v_and_b32_e32 v251, 0xffff0000, v155
	v_rcp_f32_e32 v236, v236
	v_rcp_f32_e32 v237, v237
	v_rcp_f32_e32 v238, v238
	v_rcp_f32_e32 v239, v239
	v_rcp_f32_e32 v240, v240
	v_rcp_f32_e32 v241, v241
	v_rcp_f32_e32 v242, v242
	v_rcp_f32_e32 v243, v243
	v_pk_mul_f32 v[244:245], v[236:237], v[244:245]
	v_pk_mul_f32 v[246:247], v[238:239], v[246:247]
	v_pk_mul_f32 v[248:249], v[240:241], v[248:249]
	v_pk_mul_f32 v[250:251], v[242:243], v[250:251]
	v_pk_mul_f32 v[48:49], v[48:49], v[244:245]
	v_pk_mul_f32 v[50:51], v[50:51], v[246:247]
	v_pk_mul_f32 v[44:45], v[44:45], v[248:249]
	v_pk_mul_f32 v[46:47], v[46:47], v[250:251]
	s_nop 0
	s_waitcnt vmcnt(8)
;     __device__ __forceinline__ void mid(f32x4 (&acc)[2][2][4][2], const pg8::Unit& u, int wr, int wc, int fr, int fq) const {
;     ...
;                     const u32x4 ga = *(const u32x4*)(GA + off + bj * 128), gb = *(const u32x4*)(GB + off + bj * 128);
;                     acc[ai][bj][m][0][0] *= bflo(ga.x) * __builtin_amdgcn_rcpf(bflo(gb.x)); acc[ai][bj][m][0][1] *= bfhi(ga.x) * __builtin_amdgcn_rcpf(bfhi(gb.x));
;                     acc[ai][bj][m][0][2] *= bflo(ga.y) * __builtin_amdgcn_rcpf(bflo(gb.y)); acc[ai][bj][m][0][3] *= bfhi(ga.y) * __builtin_amdgcn_rcpf(bfhi(gb.y));
;                     acc[ai][bj][m][1][0] *= bflo(ga.z) * __builtin_amdgcn_rcpf(bflo(gb.z)); acc[ai][bj][m][1][1] *= bfhi(ga.z) * __builtin_amdgcn_rcpf(bfhi(gb.z));
;                     acc[ai][bj][m][1][2] *= bflo(ga.w) * __builtin_amdgcn_rcpf(bflo(gb.w)); acc[ai][bj][m][1][3] *= bfhi(ga.w) * __builtin_amdgcn_rcpf(bfhi(gb.w));
;                     asm volatile("" : "+v"(acc[ai][bj][m][0]), "+v"(acc[ai][bj][m][1]));
;                     asm volatile("" ::: "memory");
	v_lshlrev_b32_e32 v236, 16, v156
	v_and_b32_e32 v237, 0xffff0000, v156
	v_lshlrev_b32_e32 v238, 16, v157
	v_and_b32_e32 v239, 0xffff0000, v157
	v_lshlrev_b32_e32 v240, 16, v158
	v_and_b32_e32 v241, 0xffff0000, v158
	v_lshlrev_b32_e32 v242, 16, v159
	v_and_b32_e32 v243, 0xffff0000, v159
	v_lshlrev_b32_e32 v244, 16, v160
	v_and_b32_e32 v245, 0xffff0000, v160
	v_lshlrev_b32_e32 v246, 16, v161
	v_and_b32_e32 v247, 0xffff0000, v161
	v_lshlrev_b32_e32 v248, 16, v162
	v_and_b32_e32 v249, 0xffff0000, v162
	v_lshlrev_b32_e32 v250, 16, v163
	v_and_b32_e32 v251, 0xffff0000, v163
	v_rcp_f32_e32 v236, v236
	v_rcp_f32_e32 v237, v237
	v_rcp_f32_e32 v238, v238
	v_rcp_f32_e32 v239, v239
	v_rcp_f32_e32 v240, v240
	v_rcp_f32_e32 v241, v241
	v_rcp_f32_e32 v242, v242
	v_rcp_f32_e32 v243, v243
	v_pk_mul_f32 v[244:245], v[236:237], v[244:245]
	v_pk_mul_f32 v[246:247], v[238:239], v[246:247]
	v_pk_mul_f32 v[248:249], v[240:241], v[248:249]
	v_pk_mul_f32 v[250:251], v[242:243], v[250:251]
	v_pk_mul_f32 v[40:41], v[40:41], v[244:245]
	v_pk_mul_f32 v[42:43], v[42:43], v[246:247]
	v_pk_mul_f32 v[36:37], v[36:37], v[248:249]
	v_pk_mul_f32 v[38:39], v[38:39], v[250:251]
	s_nop 0
	s_waitcnt vmcnt(6)
	v_lshlrev_b32_e32 v236, 16, v164
	v_and_b32_e32 v237, 0xffff0000, v164
	v_lshlrev_b32_e32 v238, 16, v165
	v_and_b32_e32 v239, 0xffff0000, v165
	v_lshlrev_b32_e32 v240, 16, v166
	v_and_b32_e32 v241, 0xffff0000, v166
	v_lshlrev_b32_e32 v242, 16, v167
	v_and_b32_e32 v243, 0xffff0000, v167
	v_lshlrev_b32_e32 v244, 16, v168
	v_and_b32_e32 v245, 0xffff0000, v168
	v_lshlrev_b32_e32 v246, 16, v169
	v_and_b32_e32 v247, 0xffff0000, v169
	v_lshlrev_b32_e32 v248, 16, v170
	v_and_b32_e32 v249, 0xffff0000, v170
	v_lshlrev_b32_e32 v250, 16, v171
	v_and_b32_e32 v251, 0xffff0000, v171
	v_rcp_f32_e32 v236, v236
	v_rcp_f32_e32 v237, v237
	v_rcp_f32_e32 v238, v238
	v_rcp_f32_e32 v239, v239
	v_rcp_f32_e32 v240, v240
	v_rcp_f32_e32 v241, v241
	v_rcp_f32_e32 v242, v242
	v_rcp_f32_e32 v243, v243
	v_pk_mul_f32 v[244:245], v[236:237], v[244:245]
	v_pk_mul_f32 v[246:247], v[238:239], v[246:247]
	v_pk_mul_f32 v[248:249], v[240:241], v[248:249]
	v_pk_mul_f32 v[250:251], v[242:243], v[250:251]
	v_pk_mul_f32 v[32:33], v[32:33], v[244:245]
	v_pk_mul_f32 v[34:35], v[34:35], v[246:247]
	v_pk_mul_f32 v[28:29], v[28:29], v[248:249]
	v_pk_mul_f32 v[30:31], v[30:31], v[250:251]
	s_nop 0
	s_waitcnt vmcnt(4)
	v_lshlrev_b32_e32 v236, 16, v172
	v_and_b32_e32 v237, 0xffff0000, v172
	v_lshlrev_b32_e32 v238, 16, v173
	v_and_b32_e32 v239, 0xffff0000, v173
	v_lshlrev_b32_e32 v240, 16, v174
	v_and_b32_e32 v241, 0xffff0000, v174
	v_lshlrev_b32_e32 v242, 16, v175
	v_and_b32_e32 v243, 0xffff0000, v175
	v_lshlrev_b32_e32 v244, 16, v176
	v_and_b32_e32 v245, 0xffff0000, v176
	v_lshlrev_b32_e32 v246, 16, v177
	v_and_b32_e32 v247, 0xffff0000, v177
	v_lshlrev_b32_e32 v248, 16, v178
	v_and_b32_e32 v249, 0xffff0000, v178
	v_lshlrev_b32_e32 v250, 16, v179
	v_and_b32_e32 v251, 0xffff0000, v179
	v_rcp_f32_e32 v236, v236
	v_rcp_f32_e32 v237, v237
	v_rcp_f32_e32 v238, v238
	v_rcp_f32_e32 v239, v239
	v_rcp_f32_e32 v240, v240
	v_rcp_f32_e32 v241, v241
	v_rcp_f32_e32 v242, v242
	v_rcp_f32_e32 v243, v243
	v_pk_mul_f32 v[244:245], v[236:237], v[244:245]
	v_pk_mul_f32 v[246:247], v[238:239], v[246:247]
	v_pk_mul_f32 v[248:249], v[240:241], v[248:249]
	v_pk_mul_f32 v[250:251], v[242:243], v[250:251]
	v_pk_mul_f32 v[24:25], v[24:25], v[244:245]
	v_pk_mul_f32 v[26:27], v[26:27], v[246:247]
	v_pk_mul_f32 v[20:21], v[20:21], v[248:249]
	v_pk_mul_f32 v[22:23], v[22:23], v[250:251]
	s_nop 0
	s_waitcnt vmcnt(2)
	v_lshlrev_b32_e32 v236, 16, v180
	v_and_b32_e32 v237, 0xffff0000, v180
	v_lshlrev_b32_e32 v238, 16, v181
	v_and_b32_e32 v239, 0xffff0000, v181
	v_lshlrev_b32_e32 v240, 16, v182
	v_and_b32_e32 v241, 0xffff0000, v182
	v_lshlrev_b32_e32 v242, 16, v183
	v_and_b32_e32 v243, 0xffff0000, v183
	v_lshlrev_b32_e32 v244, 16, v184
	v_and_b32_e32 v245, 0xffff0000, v184
	v_lshlrev_b32_e32 v246, 16, v185
	v_and_b32_e32 v247, 0xffff0000, v185
	v_lshlrev_b32_e32 v248, 16, v186
	v_and_b32_e32 v249, 0xffff0000, v186
	v_lshlrev_b32_e32 v250, 16, v187
	v_and_b32_e32 v251, 0xffff0000, v187
	v_rcp_f32_e32 v236, v236
	v_rcp_f32_e32 v237, v237
	v_rcp_f32_e32 v238, v238
	v_rcp_f32_e32 v239, v239
	v_rcp_f32_e32 v240, v240
	v_rcp_f32_e32 v241, v241
	v_rcp_f32_e32 v242, v242
	v_rcp_f32_e32 v243, v243
	v_pk_mul_f32 v[244:245], v[236:237], v[244:245]
	v_pk_mul_f32 v[246:247], v[238:239], v[246:247]
	v_pk_mul_f32 v[248:249], v[240:241], v[248:249]
	v_pk_mul_f32 v[250:251], v[242:243], v[250:251]
	v_pk_mul_f32 v[16:17], v[16:17], v[244:245]
	v_pk_mul_f32 v[18:19], v[18:19], v[246:247]
	v_pk_mul_f32 v[12:13], v[12:13], v[248:249]
	v_pk_mul_f32 v[14:15], v[14:15], v[250:251]
	s_nop 0
	s_waitcnt vmcnt(0)
	v_lshlrev_b32_e32 v236, 16, v188
	v_and_b32_e32 v237, 0xffff0000, v188
	v_lshlrev_b32_e32 v238, 16, v189
	v_and_b32_e32 v239, 0xffff0000, v189
	v_lshlrev_b32_e32 v240, 16, v190
	v_and_b32_e32 v241, 0xffff0000, v190
	v_lshlrev_b32_e32 v242, 16, v191
	v_and_b32_e32 v243, 0xffff0000, v191
	v_lshlrev_b32_e32 v244, 16, v192
	v_and_b32_e32 v245, 0xffff0000, v192
	v_lshlrev_b32_e32 v246, 16, v193
	v_and_b32_e32 v247, 0xffff0000, v193
	v_lshlrev_b32_e32 v248, 16, v194
	v_and_b32_e32 v249, 0xffff0000, v194
	v_lshlrev_b32_e32 v250, 16, v195
	v_and_b32_e32 v251, 0xffff0000, v195
	v_rcp_f32_e32 v236, v236
	v_rcp_f32_e32 v237, v237
	v_rcp_f32_e32 v238, v238
	v_rcp_f32_e32 v239, v239
	v_rcp_f32_e32 v240, v240
	v_rcp_f32_e32 v241, v241
	v_rcp_f32_e32 v242, v242
	v_rcp_f32_e32 v243, v243
	v_pk_mul_f32 v[244:245], v[236:237], v[244:245]
	v_pk_mul_f32 v[246:247], v[238:239], v[246:247]
	v_pk_mul_f32 v[248:249], v[240:241], v[248:249]
	v_pk_mul_f32 v[250:251], v[242:243], v[250:251]
	v_pk_mul_f32 v[8:9], v[8:9], v[244:245]
	v_pk_mul_f32 v[10:11], v[10:11], v[246:247]
	v_pk_mul_f32 v[4:5], v[4:5], v[248:249]
	v_pk_mul_f32 v[6:7], v[6:7], v[250:251]
	s_nop 0
	s_cbranch_vccnz .LBB0_451
	s_barrier
	s_branch .LBB0_451

; __device__ __forceinline__ unsigned pk2(float lo, float hi) { return __builtin_bit_cast(unsigned, __builtin_convertvector((f32x2){lo, hi}, bf16x2_t)); }
;     __device__ __forceinline__ void operator()(f32x4 (&acc)[2][2][4][2], const pg8::Unit& u, int wr, int wc, int fr, int fq) const {
;         const int row0 = u.pm * 256 + wr * 64 + fr, col0 = u.pn * 256 + wc * 32 + 8 * fq;
; #pragma unroll
;         for (int ai = 0; ai < 2; ++ai)
; #pragma unroll
;             for (int m = 0; m < 4; ++m) {
;                 const size_t off = (size_t)(row0 + ai * 128 + m * 16) * DM + col0;
; #pragma unroll
;                 for (int bj = 0; bj < 2; ++bj) {
;                     const u32x4 gb = *(const u32x4*)(GB + off + bj * 128);
;                     const f32x4 v0 = acc[ai][bj][m][0], v1 = acc[ai][bj][m][1];
;                     u32x4 w;
;                     w.x = pk2(v0[0] * bflo(gb.x), v0[1] * bfhi(gb.x)); w.y = pk2(v0[2] * bflo(gb.y), v0[3] * bfhi(gb.y));
;                     w.z = pk2(v1[0] * bflo(gb.z), v1[1] * bfhi(gb.z)); w.w = pk2(v1[2] * bflo(gb.w), v1[3] * bfhi(gb.w));
;                     *(u32x4*)((char*)MG + tiled_off(row0 + ai * 128 + m * 16, col0 + bj * 128)) = w;
;                 }
;             }
;     }
.LBB0_459:
	s_add_i32 s55, s53, s74
	v_or_b32_e32 v2, s55, v140
	s_or_b32 s66, s82, s75
	v_or_b32_e32 v150, s66, v142
	v_ashrrev_i32_e32 v3, 31, v2
	v_ashrrev_i32_e32 v151, 31, v150
	v_lshlrev_b64 v[138:139], 13, v[2:3]
	v_lshl_add_u64 v[146:147], s[16:17], 0, v[138:139]
	v_lshlrev_b64 v[138:139], 1, v[150:151]
	v_lshl_add_u64 v[152:153], v[146:147], 0, v[138:139]
	global_load_dwordx4 v[160:163], v[152:153], off nt
	global_load_dwordx4 v[164:167], v[152:153], off offset:256 nt
	v_lshl_add_u64 v[242:243], v[152:153], 0, s[40:41]
	global_load_dwordx4 v[168:171], v[242:243], off nt
	global_load_dwordx4 v[172:175], v[242:243], off offset:256 nt
	v_lshl_add_u64 v[242:243], v[152:153], 0, s[42:43]
	global_load_dwordx4 v[176:179], v[242:243], off nt
	global_load_dwordx4 v[180:183], v[242:243], off offset:256 nt
	v_lshl_add_u64 v[242:243], v[152:153], 0, s[44:45]
	global_load_dwordx4 v[184:187], v[242:243], off nt
	global_load_dwordx4 v[188:191], v[242:243], off offset:256 nt
	v_lshl_add_u64 v[242:243], v[152:153], 0, s[8:9]
	global_load_dwordx4 v[192:195], v[242:243], off nt
	global_load_dwordx4 v[196:199], v[242:243], off offset:256 nt
	v_lshl_add_u64 v[242:243], v[152:153], 0, s[46:47]
	global_load_dwordx4 v[200:203], v[242:243], off nt
	global_load_dwordx4 v[204:207], v[242:243], off offset:256 nt
	v_lshl_add_u64 v[242:243], v[152:153], 0, s[48:49]
	global_load_dwordx4 v[212:215], v[242:243], off nt
	global_load_dwordx4 v[216:219], v[242:243], off offset:256 nt
	v_lshl_add_u64 v[242:243], v[152:153], 0, s[50:51]
	global_load_dwordx4 v[220:223], v[242:243], off nt
	global_load_dwordx4 v[224:227], v[242:243], off offset:256 nt
	s_bfe_u32 s53, s66, 0x10005
	s_ashr_i32 s67, s55, 1
	s_ashr_i32 s55, s66, 6
	s_and_b32 s68, s67, 0xffffffc0
	s_or_b32 s66, s53, s77
	v_lshlrev_b32_e32 v0, 1, v150
	s_lshl_b32 s71, s66, 10
	s_add_i32 s66, s68, s55
	v_lshlrev_b32_e32 v150, 6, v2
	v_lshlrev_b32_e32 v151, 2, v2
	v_and_b32_e32 v3, 48, v0
	s_ashr_i32 s67, s66, 31
	v_and_b32_e32 v0, 32, v151
	v_and_or_b32 v156, v150, s76, v3
	s_lshl_b64 s[66:67], s[66:67], 14
	s_add_u32 s66, s30, s66
	v_bitop3_b32 v157, v156, s71, v0 bitop3:0xde
	s_addc_u32 s67, s31, s67
	s_or_b32 s70, s55, 2
	s_add_i32 s68, s68, s70
	s_ashr_i32 s69, s68, 31
	s_lshl_b64 s[68:69], s[68:69], 14
	s_add_u32 s68, s30, s68
	s_addc_u32 s69, s31, s69
	s_waitcnt vmcnt(15)
	v_lshlrev_b32_e32 v228, 16, v160
	v_and_b32_e32 v229, 0xffff0000, v160
	v_lshlrev_b32_e32 v230, 16, v161
	v_and_b32_e32 v231, 0xffff0000, v161
	v_lshlrev_b32_e32 v232, 16, v162
	v_and_b32_e32 v233, 0xffff0000, v162
	v_lshlrev_b32_e32 v234, 16, v163
	v_and_b32_e32 v235, 0xffff0000, v163
	v_pk_mul_f32 v[128:129], v[128:129], v[228:229]
	v_pk_mul_f32 v[130:131], v[130:131], v[230:231]
	v_pk_mul_f32 v[124:125], v[124:125], v[232:233]
	v_pk_mul_f32 v[126:127], v[126:127], v[234:235]
	v_mov_b32_e32 v240, v157
	v_cvt_pk_bf16_f32 v236, v128, v129
	v_cvt_pk_bf16_f32 v237, v130, v131
	v_cvt_pk_bf16_f32 v238, v124, v125
	v_cvt_pk_bf16_f32 v239, v126, v127
	global_store_dwordx4 v240, v[236:239], s[66:67]
	s_waitcnt vmcnt(15)
	v_lshlrev_b32_e32 v228, 16, v164
	v_and_b32_e32 v229, 0xffff0000, v164
	v_lshlrev_b32_e32 v230, 16, v165
	v_and_b32_e32 v231, 0xffff0000, v165
	v_lshlrev_b32_e32 v232, 16, v166
	v_and_b32_e32 v233, 0xffff0000, v166
	v_lshlrev_b32_e32 v234, 16, v167
	v_and_b32_e32 v235, 0xffff0000, v167
	v_pk_mul_f32 v[120:121], v[120:121], v[228:229]
	v_pk_mul_f32 v[122:123], v[122:123], v[230:231]
	v_pk_mul_f32 v[116:117], v[116:117], v[232:233]
	v_pk_mul_f32 v[118:119], v[118:119], v[234:235]
	v_cvt_pk_bf16_f32 v236, v120, v121
	v_cvt_pk_bf16_f32 v237, v122, v123
	v_cvt_pk_bf16_f32 v238, v116, v117
	v_cvt_pk_bf16_f32 v239, v118, v119
	global_store_dwordx4 v240, v[236:239], s[68:69]
	s_waitcnt vmcnt(15)
	v_lshlrev_b32_e32 v228, 16, v168
	v_and_b32_e32 v229, 0xffff0000, v168
	v_lshlrev_b32_e32 v230, 16, v169
	v_and_b32_e32 v231, 0xffff0000, v169
	v_lshlrev_b32_e32 v232, 16, v170
	v_and_b32_e32 v233, 0xffff0000, v170
	v_lshlrev_b32_e32 v234, 16, v171
	v_and_b32_e32 v235, 0xffff0000, v171
	v_pk_mul_f32 v[112:113], v[112:113], v[228:229]
	v_pk_mul_f32 v[114:115], v[114:115], v[230:231]
	v_pk_mul_f32 v[108:109], v[108:109], v[232:233]
	v_pk_mul_f32 v[110:111], v[110:111], v[234:235]
	v_add_u32_e32 v240, 0x800, v157
	v_cvt_pk_bf16_f32 v236, v112, v113
	v_cvt_pk_bf16_f32 v237, v114, v115
	v_cvt_pk_bf16_f32 v238, v108, v109
	v_cvt_pk_bf16_f32 v239, v110, v111
	global_store_dwordx4 v240, v[236:239], s[66:67]
	s_waitcnt vmcnt(15)
	v_lshlrev_b32_e32 v228, 16, v172
	v_and_b32_e32 v229, 0xffff0000, v172
	v_lshlrev_b32_e32 v230, 16, v173
	v_and_b32_e32 v231, 0xffff0000, v173
	v_lshlrev_b32_e32 v232, 16, v174
	v_and_b32_e32 v233, 0xffff0000, v174
	v_lshlrev_b32_e32 v234, 16, v175
	v_and_b32_e32 v235, 0xffff0000, v175
	v_pk_mul_f32 v[104:105], v[104:105], v[228:229]
	v_pk_mul_f32 v[106:107], v[106:107], v[230:231]
	v_pk_mul_f32 v[100:101], v[100:101], v[232:233]
	v_pk_mul_f32 v[102:103], v[102:103], v[234:235]
	v_cvt_pk_bf16_f32 v236, v104, v105
	v_cvt_pk_bf16_f32 v237, v106, v107
	v_cvt_pk_bf16_f32 v238, v100, v101
	v_cvt_pk_bf16_f32 v239, v102, v103
	global_store_dwordx4 v240, v[236:239], s[68:69]
	s_waitcnt vmcnt(15)
	v_lshlrev_b32_e32 v228, 16, v176
	v_and_b32_e32 v229, 0xffff0000, v176
	v_lshlrev_b32_e32 v230, 16, v177
	v_and_b32_e32 v231, 0xffff0000, v177
	v_lshlrev_b32_e32 v232, 16, v178
	v_and_b32_e32 v233, 0xffff0000, v178
	v_lshlrev_b32_e32 v234, 16, v179
	v_and_b32_e32 v235, 0xffff0000, v179
	v_pk_mul_f32 v[96:97], v[96:97], v[228:229]
	v_pk_mul_f32 v[98:99], v[98:99], v[230:231]
	v_pk_mul_f32 v[92:93], v[92:93], v[232:233]
	v_pk_mul_f32 v[94:95], v[94:95], v[234:235]
	v_add_u32_e32 v240, 0x1000, v157
	v_cvt_pk_bf16_f32 v236, v96, v97
	v_cvt_pk_bf16_f32 v237, v98, v99
	v_cvt_pk_bf16_f32 v238, v92, v93
	v_cvt_pk_bf16_f32 v239, v94, v95
	global_store_dwordx4 v240, v[236:239], s[66:67]
	s_waitcnt vmcnt(15)
; __device__ __forceinline__ unsigned pk2(float lo, float hi) { return __builtin_bit_cast(unsigned, __builtin_convertvector((f32x2){lo, hi}, bf16x2_t)); }
;     __device__ __forceinline__ void operator()(f32x4 (&acc)[2][2][4][2], const pg8::Unit& u, int wr, int wc, int fr, int fq) const {
;     ...
;                     const u32x4 gb = *(const u32x4*)(GB + off + bj * 128);
;                     const f32x4 v0 = acc[ai][bj][m][0], v1 = acc[ai][bj][m][1];
;                     u32x4 w;
;                     w.x = pk2(v0[0] * bflo(gb.x), v0[1] * bfhi(gb.x)); w.y = pk2(v0[2] * bflo(gb.y), v0[3] * bfhi(gb.y));
;                     w.z = pk2(v1[0] * bflo(gb.z), v1[1] * bfhi(gb.z)); w.w = pk2(v1[2] * bflo(gb.w), v1[3] * bfhi(gb.w));
;                     *(u32x4*)((char*)MG + tiled_off(row0 + ai * 128 + m * 16, col0 + bj * 128)) = w;
	v_lshlrev_b32_e32 v228, 16, v180
	v_and_b32_e32 v229, 0xffff0000, v180
	v_lshlrev_b32_e32 v230, 16, v181
	v_and_b32_e32 v231, 0xffff0000, v181
	v_lshlrev_b32_e32 v232, 16, v182
	v_and_b32_e32 v233, 0xffff0000, v182
	v_lshlrev_b32_e32 v234, 16, v183
	v_and_b32_e32 v235, 0xffff0000, v183
	v_pk_mul_f32 v[88:89], v[88:89], v[228:229]
	v_pk_mul_f32 v[90:91], v[90:91], v[230:231]
	v_pk_mul_f32 v[84:85], v[84:85], v[232:233]
	v_pk_mul_f32 v[86:87], v[86:87], v[234:235]
	v_cvt_pk_bf16_f32 v236, v88, v89
	v_cvt_pk_bf16_f32 v237, v90, v91
	v_cvt_pk_bf16_f32 v238, v84, v85
	v_cvt_pk_bf16_f32 v239, v86, v87
	global_store_dwordx4 v240, v[236:239], s[68:69]
	s_waitcnt vmcnt(15)
	v_lshlrev_b32_e32 v228, 16, v184
	v_and_b32_e32 v229, 0xffff0000, v184
	v_lshlrev_b32_e32 v230, 16, v185
	v_and_b32_e32 v231, 0xffff0000, v185
	v_lshlrev_b32_e32 v232, 16, v186
	v_and_b32_e32 v233, 0xffff0000, v186
	v_lshlrev_b32_e32 v234, 16, v187
	v_and_b32_e32 v235, 0xffff0000, v187
	v_pk_mul_f32 v[80:81], v[80:81], v[228:229]
	v_pk_mul_f32 v[82:83], v[82:83], v[230:231]
	v_pk_mul_f32 v[76:77], v[76:77], v[232:233]
	v_pk_mul_f32 v[78:79], v[78:79], v[234:235]
	v_add_u32_e32 v240, 0x1800, v157
	v_cvt_pk_bf16_f32 v236, v80, v81
	v_cvt_pk_bf16_f32 v237, v82, v83
	v_cvt_pk_bf16_f32 v238, v76, v77
	v_cvt_pk_bf16_f32 v239, v78, v79
	global_store_dwordx4 v240, v[236:239], s[66:67]
	s_waitcnt vmcnt(15)
	v_lshlrev_b32_e32 v228, 16, v188
	v_and_b32_e32 v229, 0xffff0000, v188
	v_lshlrev_b32_e32 v230, 16, v189
	v_and_b32_e32 v231, 0xffff0000, v189
	v_lshlrev_b32_e32 v232, 16, v190
	v_and_b32_e32 v233, 0xffff0000, v190
	v_lshlrev_b32_e32 v234, 16, v191
	v_and_b32_e32 v235, 0xffff0000, v191
	v_pk_mul_f32 v[72:73], v[72:73], v[228:229]
	v_pk_mul_f32 v[74:75], v[74:75], v[230:231]
	v_pk_mul_f32 v[68:69], v[68:69], v[232:233]
	v_pk_mul_f32 v[70:71], v[70:71], v[234:235]
	v_cvt_pk_bf16_f32 v236, v72, v73
	v_cvt_pk_bf16_f32 v237, v74, v75
	v_cvt_pk_bf16_f32 v238, v68, v69
	v_cvt_pk_bf16_f32 v239, v70, v71
	global_store_dwordx4 v240, v[236:239], s[68:69]
	s_waitcnt vmcnt(15)
	v_lshlrev_b32_e32 v228, 16, v192
	v_and_b32_e32 v229, 0xffff0000, v192
	v_lshlrev_b32_e32 v230, 16, v193
	v_and_b32_e32 v231, 0xffff0000, v193
	v_lshlrev_b32_e32 v232, 16, v194
	v_and_b32_e32 v233, 0xffff0000, v194
	v_lshlrev_b32_e32 v234, 16, v195
	v_and_b32_e32 v235, 0xffff0000, v195
	v_pk_mul_f32 v[64:65], v[64:65], v[228:229]
	v_pk_mul_f32 v[66:67], v[66:67], v[230:231]
	v_pk_mul_f32 v[60:61], v[60:61], v[232:233]
	v_pk_mul_f32 v[62:63], v[62:63], v[234:235]
	v_add_u32_e32 v240, 0x100000, v157
	v_cvt_pk_bf16_f32 v236, v64, v65
	v_cvt_pk_bf16_f32 v237, v66, v67
	v_cvt_pk_bf16_f32 v238, v60, v61
	v_cvt_pk_bf16_f32 v239, v62, v63
	global_store_dwordx4 v240, v[236:239], s[66:67]
	s_waitcnt vmcnt(15)
	v_lshlrev_b32_e32 v228, 16, v196
	v_and_b32_e32 v229, 0xffff0000, v196
	v_lshlrev_b32_e32 v230, 16, v197
	v_and_b32_e32 v231, 0xffff0000, v197
	v_lshlrev_b32_e32 v232, 16, v198
	v_and_b32_e32 v233, 0xffff0000, v198
	v_lshlrev_b32_e32 v234, 16, v199
	v_and_b32_e32 v235, 0xffff0000, v199
	v_pk_mul_f32 v[56:57], v[56:57], v[228:229]
	v_pk_mul_f32 v[58:59], v[58:59], v[230:231]
	v_pk_mul_f32 v[52:53], v[52:53], v[232:233]
	v_pk_mul_f32 v[54:55], v[54:55], v[234:235]
	v_cvt_pk_bf16_f32 v236, v56, v57
	v_cvt_pk_bf16_f32 v237, v58, v59
	v_cvt_pk_bf16_f32 v238, v52, v53
	v_cvt_pk_bf16_f32 v239, v54, v55
	global_store_dwordx4 v240, v[236:239], s[68:69]
	s_waitcnt vmcnt(15)
	v_lshlrev_b32_e32 v228, 16, v200
	v_and_b32_e32 v229, 0xffff0000, v200
	v_lshlrev_b32_e32 v230, 16, v201
	v_and_b32_e32 v231, 0xffff0000, v201
	v_lshlrev_b32_e32 v232, 16, v202
	v_and_b32_e32 v233, 0xffff0000, v202
	v_lshlrev_b32_e32 v234, 16, v203
	v_and_b32_e32 v235, 0xffff0000, v203
	v_pk_mul_f32 v[48:49], v[48:49], v[228:229]
	v_pk_mul_f32 v[50:51], v[50:51], v[230:231]
	v_pk_mul_f32 v[44:45], v[44:45], v[232:233]
	v_pk_mul_f32 v[46:47], v[46:47], v[234:235]
	v_add_u32_e32 v240, 0x100800, v157
	v_cvt_pk_bf16_f32 v236, v48, v49
	v_cvt_pk_bf16_f32 v237, v50, v51
	v_cvt_pk_bf16_f32 v238, v44, v45
	v_cvt_pk_bf16_f32 v239, v46, v47
	global_store_dwordx4 v240, v[236:239], s[66:67]
	s_waitcnt vmcnt(15)
; __device__ __forceinline__ unsigned pk2(float lo, float hi) { return __builtin_bit_cast(unsigned, __builtin_convertvector((f32x2){lo, hi}, bf16x2_t)); }
;     __device__ __forceinline__ void operator()(f32x4 (&acc)[2][2][4][2], const pg8::Unit& u, int wr, int wc, int fr, int fq) const {
;     ...
;                     const u32x4 gb = *(const u32x4*)(GB + off + bj * 128);
;                     const f32x4 v0 = acc[ai][bj][m][0], v1 = acc[ai][bj][m][1];
;                     u32x4 w;
;                     w.x = pk2(v0[0] * bflo(gb.x), v0[1] * bfhi(gb.x)); w.y = pk2(v0[2] * bflo(gb.y), v0[3] * bfhi(gb.y));
;                     w.z = pk2(v1[0] * bflo(gb.z), v1[1] * bfhi(gb.z)); w.w = pk2(v1[2] * bflo(gb.w), v1[3] * bfhi(gb.w));
;                     *(u32x4*)((char*)MG + tiled_off(row0 + ai * 128 + m * 16, col0 + bj * 128)) = w;
	v_lshlrev_b32_e32 v228, 16, v204
	v_and_b32_e32 v229, 0xffff0000, v204
	v_lshlrev_b32_e32 v230, 16, v205
	v_and_b32_e32 v231, 0xffff0000, v205
	v_lshlrev_b32_e32 v232, 16, v206
	v_and_b32_e32 v233, 0xffff0000, v206
	v_lshlrev_b32_e32 v234, 16, v207
	v_and_b32_e32 v235, 0xffff0000, v207
	v_pk_mul_f32 v[40:41], v[40:41], v[228:229]
	v_pk_mul_f32 v[42:43], v[42:43], v[230:231]
	v_pk_mul_f32 v[36:37], v[36:37], v[232:233]
	v_pk_mul_f32 v[38:39], v[38:39], v[234:235]
	v_cvt_pk_bf16_f32 v236, v40, v41
	v_cvt_pk_bf16_f32 v237, v42, v43
	v_cvt_pk_bf16_f32 v238, v36, v37
	v_cvt_pk_bf16_f32 v239, v38, v39
	global_store_dwordx4 v240, v[236:239], s[68:69]
	s_waitcnt vmcnt(15)
	v_lshlrev_b32_e32 v228, 16, v212
	v_and_b32_e32 v229, 0xffff0000, v212
	v_lshlrev_b32_e32 v230, 16, v213
	v_and_b32_e32 v231, 0xffff0000, v213
	v_lshlrev_b32_e32 v232, 16, v214
	v_and_b32_e32 v233, 0xffff0000, v214
	v_lshlrev_b32_e32 v234, 16, v215
	v_and_b32_e32 v235, 0xffff0000, v215
	v_pk_mul_f32 v[32:33], v[32:33], v[228:229]
	v_pk_mul_f32 v[34:35], v[34:35], v[230:231]
	v_pk_mul_f32 v[28:29], v[28:29], v[232:233]
	v_pk_mul_f32 v[30:31], v[30:31], v[234:235]
	v_add_u32_e32 v240, 0x101000, v157
	v_cvt_pk_bf16_f32 v236, v32, v33
	v_cvt_pk_bf16_f32 v237, v34, v35
	v_cvt_pk_bf16_f32 v238, v28, v29
	v_cvt_pk_bf16_f32 v239, v30, v31
	global_store_dwordx4 v240, v[236:239], s[66:67]
	s_waitcnt vmcnt(15)
	v_lshlrev_b32_e32 v228, 16, v216
	v_and_b32_e32 v229, 0xffff0000, v216
	v_lshlrev_b32_e32 v230, 16, v217
	v_and_b32_e32 v231, 0xffff0000, v217
	v_lshlrev_b32_e32 v232, 16, v218
	v_and_b32_e32 v233, 0xffff0000, v218
	v_lshlrev_b32_e32 v234, 16, v219
	v_and_b32_e32 v235, 0xffff0000, v219
	v_pk_mul_f32 v[24:25], v[24:25], v[228:229]
	v_pk_mul_f32 v[26:27], v[26:27], v[230:231]
	v_pk_mul_f32 v[20:21], v[20:21], v[232:233]
	v_pk_mul_f32 v[22:23], v[22:23], v[234:235]
	v_cvt_pk_bf16_f32 v236, v24, v25
	v_cvt_pk_bf16_f32 v237, v26, v27
	v_cvt_pk_bf16_f32 v238, v20, v21
	v_cvt_pk_bf16_f32 v239, v22, v23
	global_store_dwordx4 v240, v[236:239], s[68:69]
	s_waitcnt vmcnt(15)
	v_lshlrev_b32_e32 v228, 16, v220
	v_and_b32_e32 v229, 0xffff0000, v220
	v_lshlrev_b32_e32 v230, 16, v221
	v_and_b32_e32 v231, 0xffff0000, v221
	v_lshlrev_b32_e32 v232, 16, v222
	v_and_b32_e32 v233, 0xffff0000, v222
	v_lshlrev_b32_e32 v234, 16, v223
	v_and_b32_e32 v235, 0xffff0000, v223
	v_pk_mul_f32 v[16:17], v[16:17], v[228:229]
	v_pk_mul_f32 v[18:19], v[18:19], v[230:231]
	v_pk_mul_f32 v[12:13], v[12:13], v[232:233]
	v_pk_mul_f32 v[14:15], v[14:15], v[234:235]
	v_add_u32_e32 v240, 0x101800, v157
	v_cvt_pk_bf16_f32 v236, v16, v17
	v_cvt_pk_bf16_f32 v237, v18, v19
	v_cvt_pk_bf16_f32 v238, v12, v13
	v_cvt_pk_bf16_f32 v239, v14, v15
	global_store_dwordx4 v240, v[236:239], s[66:67]
	s_waitcnt vmcnt(15)
	v_lshlrev_b32_e32 v228, 16, v224
	v_and_b32_e32 v229, 0xffff0000, v224
	v_lshlrev_b32_e32 v230, 16, v225
	v_and_b32_e32 v231, 0xffff0000, v225
	v_lshlrev_b32_e32 v232, 16, v226
	v_and_b32_e32 v233, 0xffff0000, v226
	v_lshlrev_b32_e32 v234, 16, v227
	v_and_b32_e32 v235, 0xffff0000, v227
	v_pk_mul_f32 v[8:9], v[8:9], v[228:229]
	v_pk_mul_f32 v[10:11], v[10:11], v[230:231]
	v_pk_mul_f32 v[4:5], v[4:5], v[232:233]
	v_pk_mul_f32 v[6:7], v[6:7], v[234:235]
	v_cvt_pk_bf16_f32 v236, v8, v9
	v_cvt_pk_bf16_f32 v237, v10, v11
	v_cvt_pk_bf16_f32 v238, v4, v5
	v_cvt_pk_bf16_f32 v239, v6, v7
	global_store_dwordx4 v240, v[236:239], s[68:69]
	s_andn2_b64 vcc, exec, s[0:1]
	s_mov_b64 s[0:1], -1
	s_cbranch_vccnz .LBB0_443
	s_andn2_b64 vcc, exec, s[12:13]
	s_cbranch_vccnz .LBB0_442
	s_barrier
	s_branch .LBB0_442
